# P2 and P11 tile order: 4 M-tiles x 8 N-tiles per XCD round (A operand read once from HBM)
# speedup vs baseline: 1.0040x; 1.0040x over previous
.LBB0_362:
	s_add_i32 s2, s6, s2
	s_lshr_b32 s5, s2, 5
	s_and_b32 s2, s2, 31
	s_lshl_b32 s5, s5, 2
	s_and_b32 s3, s2, 3
	s_add_i32 s79, s5, s3
	s_lshr_b32 s80, s2, 2
	s_andn2_b64 vcc, exec, s[0:1]
	s_cbranch_vccnz .LBB0_357

.LBB0_373:
	s_ashr_i32 s10, s42, 3
	s_add_i32 s10, s54, s10
	s_lshr_b32 s42, s10, 5
	s_lshl_b32 s42, s42, 2
	s_and_b32 s10, s10, 31
	s_lshr_b32 s77, s10, 2
	s_and_b32 s10, s10, 3
	s_add_i32 s78, s42, s10

.LBB0_1550:
	v_lshrrev_b32_e32 v4, 1, v0
	v_lshrrev_b32_e32 v5, 5, v0
	v_lshlrev_b32_e32 v1, 4, v0
	v_and_b32_e32 v2, 32, v0
	v_and_b32_e32 v4, 24, v4
	v_and_b32_e32 v5, 4, v5
	v_bfe_u32 v6, v0, 2, 2
	v_bfe_u32 v3, v0, 2, 4
	v_bitop3_b32 v1, v1, v2, 48 bitop3:0x6c
	v_and_b32_e32 v10, 64, v0
	v_or3_b32 v4, v5, v6, v4
	v_lshrrev_b32_e32 v5, 3, v0
	v_or_b32_e32 v2, v1, v10
	v_and_or_b32 v6, v5, 48, v3
	v_and_or_b32 v5, v5, 32, v4
	v_lshrrev_b32_e32 v2, 1, v2
	v_mul_u32_u24_e32 v5, 0x1600, v5
	s_add_u32 s22, s26, 0x11c00000
	v_or_b32_e32 v5, v5, v2
	s_addc_u32 s23, s27, 0
	v_lshlrev_b32_e32 v130, 1, v5
	v_bfe_u32 v5, v0, 3, 25
	s_add_u32 s24, s26, 0x2d00000
	v_or_b32_e32 v5, 64, v5
	s_movk_i32 s1, 0x70
	s_addc_u32 s28, s27, 0
	v_and_or_b32 v3, v5, s1, v3
	s_movk_i32 s1, 0x60
	s_add_i32 s0, s4, s0
	v_and_or_b32 v4, v5, s1, v4
	s_lshr_b32 s6, s0, 5
	s_lshl_b32 s6, s6, 2
	s_and_b32 s7, s0, 28
	s_lshl_b32 s7, s7, 1
	s_and_b32 s0, s0, 3
	s_lshr_b32 s5, s2, 6
	s_add_i32 s44, s6, s0
	s_ashr_i32 s0, s7, 3
	s_lshr_b32 s3, s2, 8
	s_lshl_b32 s29, s5, 10
	s_lshr_b32 s4, s7, 3
	s_mul_hi_i32 s1, s0, 0x2c0000
	s_mul_i32 s0, s0, 0x2c0000
	v_mul_u32_u24_e32 v12, 0x1600, v3
	s_add_u32 s20, s24, s0
	v_or_b32_e32 v3, v12, v2
	s_addc_u32 s21, s28, s1
	s_add_i32 s30, s29, 0
	v_mul_u32_u24_e32 v11, 0x1600, v6
	v_lshlrev_b32_e32 v132, 1, v3
	v_mul_u32_u24_e32 v3, 0x1600, v4
	s_add_i32 m0, s30, 0x10000
	v_or_b32_e32 v6, v2, v11
	v_or_b32_e32 v2, v3, v2
	global_load_lds_dwordx4 v130, s[20:21]
	s_add_i32 m0, s30, 0x12000
	v_lshlrev_b32_e32 v134, 1, v2
	s_add_u32 s0, s20, 0x160000
	global_load_lds_dwordx4 v134, s[20:21]
	s_addc_u32 s1, s21, 0
	s_add_i32 m0, s30, 0x14000
	s_mul_i32 s8, s44, 0x2c0000
	global_load_lds_dwordx4 v130, s[0:1]
	s_add_i32 m0, s30, 0x16000
	s_mul_hi_i32 s6, s44, 0x2c0000
	s_add_u32 s16, s22, s8
	s_addc_u32 s17, s23, s6
	s_add_i32 s31, s30, 0x2000
	v_lshlrev_b32_e32 v128, 1, v6
	global_load_lds_dwordx4 v134, s[0:1]
	s_mov_b32 m0, s30
	s_add_u32 s0, s16, 0x160000
	global_load_lds_dwordx4 v128, s[16:17]
	s_mov_b32 m0, s31
	s_addc_u32 s1, s17, 0
	s_add_i32 s34, s30, 0x4000
	global_load_lds_dwordx4 v132, s[16:17]
	s_mov_b32 m0, s34
	s_add_i32 s35, s30, 0x6000
	global_load_lds_dwordx4 v128, s[0:1]
	s_mov_b32 m0, s35
	v_mov_b32_e32 v131, 0
	global_load_lds_dwordx4 v132, s[0:1]
	v_mov_b32_e32 v135, v131
	v_mov_b32_e32 v129, v131
	v_mov_b32_e32 v133, v131
	s_cmp_eq_u32 s3, 1
	s_mov_b32 s36, 0
	v_lshl_add_u64 v[8:9], s[20:21], 0, v[130:131]
	v_lshl_add_u64 v[6:7], s[20:21], 0, v[134:135]
	v_lshl_add_u64 v[2:3], s[16:17], 0, v[128:129]
	s_cselect_b64 s[0:1], -1, 0
	s_cmp_lg_u32 s3, 1
	v_lshl_add_u64 v[4:5], s[16:17], 0, v[132:133]
	s_cbranch_scc1 .LBB0_1552
	s_barrier

.LBB0_1560:
	s_ashr_i32 s2, s14, 3
	s_add_i32 s2, s26, s2
	s_lshr_b32 s14, s2, 5
	s_lshl_b32 s14, s14, 2
	s_and_b32 s2, s2, 31
	s_lshr_b32 s42, s2, 2
	s_and_b32 s2, s2, 3
	s_add_i32 s43, s14, s2
